# MLA tile loop: waves 4-7 start each tile 512 cycles late (s_sleep 8) so SIMD partner waves overlap MFMA with softmax VALU
# baseline (speedup 1.0000x reference)
; #define LAS __attribute__((address_space(3)))
; DI float shx(float v, int lane, int m) { return __builtin_bit_cast(float, __builtin_amdgcn_ds_bpermute((lane ^ m) << 2, __builtin_bit_cast(int, v))); }
; #define MFMA32(a, b, c) __builtin_amdgcn_mfma_f32_32x32x16_bf16((a), (b), (c), 0, 0, 0)
; #define MLA_LOAD(T) do { const size_t kr_ = (size_t)(kvbase + 64 * (T)); \
;         gk = *(const u32x4*)(KN + (kr_ + lk) * 512 + head * 64 + lc * 8); gv = *(const u32x4*)(VM + (kr_ + lk) * 512 + head * 64 + lc * 8); \
;         if (tid < 256) gr = *(const u32x4*)(KRb + (kr_ + rkk) * 32 + rc * 8); } while (0)
; DI void mla_item(int g_wave, LAS unsigned char* lds, const bf16_t* QN, const bf16_t* QR, const bf16_t* KN, const bf16_t* KRb, const bf16_t* VM, bf16_t* MIX,
;                  int kvbase, int qrow0, int nq, int head, int ntiles, int wt) {
;     ...
;     for (int T = 0; T < ntiles; ++T) {
;         if (T + 1 < ntiles) MLA_LOAD(T + 1);
;         if (T < wt) {
;             LAS const unsigned char* base = lds + (T & 1) * BUF;
;             f32x16 s0, s1;
; #pragma unroll
;             for (int i = 0; i < 16; ++i) { s0[i] = 0.f; s1[i] = 0.f; }
; #pragma unroll
;             for (int s = 0; s < 6; ++s) {
;                 const bf16x8 a0 = *(LAS const bf16x8*)(base + r * KST + (16 * s + 8 * h) * 2);
;                 const bf16x8 a1 = *(LAS const bf16x8*)(base + (32 + r) * KST + (16 * s + 8 * h) * 2);
;                 s0 = MFMA32(a0, qf[s], s0); s1 = MFMA32(a1, qf[s], s1);
;             }
;             float mx = s0[0];
; #pragma unroll
;             for (int i = 0; i < 16; ++i) { mx = fmaxf(mx, s0[i]); mx = fmaxf(mx, s1[i]); }
;             mx = fmaxf(mx, shx(mx, lane, 32));
.LBB0_1012:
	s_or_b64 exec, exec, s[4:5]
	v_cmp_lt_i32_e32 vcc, s7, v118
	s_and_saveexec_b64 s[4:5], vcc
	s_cbranch_execz .LBB0_1014
	s_cmp_lt_u32 s21, 4
	s_cbranch_scc1 .Lmla_nostag
	s_sleep 8
.Lmla_nostag:
	s_bitcmp1_b32 s7, 0
	s_cselect_b32 s8, 0x5800, 0
	s_add_i32 s8, s8, 0
	v_add3_u32 v109, s8, v122, v100
	ds_read_b128 v[32:35], v109 offset:6656
	ds_read_b128 v[36:39], v109
	ds_read_b128 v[110:113], v109 offset:32
	ds_read_b128 v[124:127], v109 offset:6688
	s_waitcnt lgkmcnt(2)
	v_mfma_f32_32x32x16_bf16 v[48:63], v[36:39], v[84:87], 0
	v_mfma_f32_32x32x16_bf16 v[32:47], v[32:35], v[84:87], 0
	s_waitcnt lgkmcnt(1)
	v_mfma_f32_32x32x16_bf16 v[48:63], v[110:113], v[80:83], v[48:63]
	s_waitcnt lgkmcnt(0)
	v_mfma_f32_32x32x16_bf16 v[32:47], v[124:127], v[80:83], v[32:47]
	ds_read_b128 v[110:113], v109 offset:64
	ds_read_b128 v[124:127], v109 offset:6720
	s_waitcnt lgkmcnt(1)
	v_mfma_f32_32x32x16_bf16 v[48:63], v[110:113], v[76:79], v[48:63]
	s_waitcnt lgkmcnt(0)
	v_mfma_f32_32x32x16_bf16 v[32:47], v[124:127], v[76:79], v[32:47]
	ds_read_b128 v[110:113], v109 offset:96
	ds_read_b128 v[124:127], v109 offset:6752
	s_waitcnt lgkmcnt(1)
	v_mfma_f32_32x32x16_bf16 v[48:63], v[110:113], v[68:71], v[48:63]
	s_waitcnt lgkmcnt(0)
	v_mfma_f32_32x32x16_bf16 v[32:47], v[124:127], v[68:71], v[32:47]
	ds_read_b128 v[110:113], v109 offset:128
	ds_read_b128 v[124:127], v109 offset:6784
	s_waitcnt lgkmcnt(1)
	v_mfma_f32_32x32x16_bf16 v[48:63], v[110:113], v[72:75], v[48:63]
	s_waitcnt lgkmcnt(0)
	v_mfma_f32_32x32x16_bf16 v[32:47], v[124:127], v[72:75], v[32:47]
	ds_read_b128 v[110:113], v109 offset:160
	ds_read_b128 v[124:127], v109 offset:6816
	s_waitcnt lgkmcnt(1)
	v_mfma_f32_32x32x16_bf16 v[48:63], v[110:113], v[64:67], v[48:63]
	s_waitcnt lgkmcnt(0)
	v_mfma_f32_32x32x16_bf16 v[32:47], v[124:127], v[64:67], v[32:47]
	s_nop 9
	v_max_f32_e32 v110, v48, v48
	s_nop 0
	v_max_f32_e32 v109, v32, v32
	v_max_f32_e32 v109, v110, v109
	v_max3_f32 v109, v109, v49, v33
	v_max3_f32 v109, v109, v50, v34
	v_max3_f32 v109, v109, v51, v35
	v_max3_f32 v109, v109, v52, v36
	v_max3_f32 v109, v109, v53, v37
	v_max3_f32 v109, v109, v54, v38
	v_max3_f32 v109, v109, v55, v39
	v_max3_f32 v109, v109, v56, v40
	v_max3_f32 v109, v109, v57, v41
	v_max3_f32 v109, v109, v58, v42
	v_max3_f32 v109, v109, v59, v43
	v_max3_f32 v109, v109, v60, v44
	v_max3_f32 v109, v109, v61, v45
	v_max3_f32 v109, v109, v62, v46
	v_max3_f32 v109, v109, v63, v47
	ds_bpermute_b32 v110, v103, v109
	s_waitcnt lgkmcnt(0)
; #define LAS __attribute__((address_space(3)))
; DI float ex2(float x) { return __builtin_amdgcn_exp2f(x); }
; DI float shx(float v, int lane, int m) { return __builtin_bit_cast(float, __builtin_amdgcn_ds_bpermute((lane ^ m) << 2, __builtin_bit_cast(int, v))); }
; #define MFMA32(a, b, c) __builtin_amdgcn_mfma_f32_32x32x16_bf16((a), (b), (c), 0, 0, 0)
; DI bf16x8 tr_frag(LAS const unsigned char* p, int hi_off) { s16x4 lo = trr(p), hi = trr(p + hi_off); return __builtin_shufflevector(lo, hi, 0, 1, 2, 3, 4, 5, 6, 7); }
; DI void mla_item(int g_wave, LAS unsigned char* lds, const bf16_t* QN, const bf16_t* QR, const bf16_t* KN, const bf16_t* KRb, const bf16_t* VM, bf16_t* MIX,
;                  int kvbase, int qrow0, int nq, int head, int ntiles, int wt) {
;     ...
;             mx = fmaxf(mx, shx(mx, lane, 32));
;             const float m_new = fmaxf(m_run, mx), alpha = ex2(m_run - m_new);
;             m_run = m_new;
;             float ls = 0.f;
; #pragma unroll
;             for (int i = 0; i < 16; ++i) { s0[i] = ex2(s0[i] - m_new); s1[i] = ex2(s1[i] - m_new); ls += s0[i] + s1[i]; }
;             l_run = l_run * alpha + ls;
; #pragma unroll
;             for (int i = 0; i < 16; ++i) { o0[i] *= alpha; o1[i] *= alpha; }
;             LAS const unsigned char* vb = base + KB;
; #pragma unroll
;             for (int kt = 0; kt < 2; ++kt)
; #pragma unroll
;                 for (int ss = 0; ss < 2; ++ss) {
;                     const bf16x8 pb = packfrag(kt == 0 ? s0 : s1, ss);
;                     LAS const unsigned char* vp = vb + (32 * kt + 16 * ss + 4 * h + tq) * VST + (16 * blk + 4 * tp) * 2;
;                     const bf16x8 a0 = tr_frag(vp, 8 * VST), a1 = tr_frag(vp + 64, 8 * VST);
;                     o0 = MFMA32(a0, pb, o0); o1 = MFMA32(a1, pb, o1);
;                 }
	v_max3_f32 v124, v108, v109, v110
	v_sub_f32_e32 v32, v32, v124
	v_exp_f32_e32 v125, v32
	v_sub_f32_e32 v32, v49, v124
	v_sub_f32_e32 v132, v108, v124
	v_exp_f32_e32 v108, v32
	v_sub_f32_e32 v32, v33, v124
	v_sub_f32_e32 v33, v50, v124
	v_exp_f32_e32 v134, v33
	v_sub_f32_e32 v33, v34, v124
	v_exp_f32_e32 v126, v33
	v_sub_f32_e32 v33, v51, v124
	v_sub_f32_e32 v48, v48, v124
	v_exp_f32_e32 v110, v33
	v_sub_f32_e32 v33, v35, v124
	v_exp_f32_e32 v133, v48
	v_exp_f32_e32 v48, v33
	v_sub_f32_e32 v33, v52, v124
	v_exp_f32_e32 v135, v33
	v_sub_f32_e32 v33, v36, v124
	v_exp_f32_e32 v127, v33
	v_sub_f32_e32 v33, v53, v124
	v_exp_f32_e32 v112, v33
	v_sub_f32_e32 v33, v37, v124
	v_exp_f32_e32 v50, v33
	v_sub_f32_e32 v33, v54, v124
	v_exp_f32_e32 v136, v33
	v_sub_f32_e32 v33, v38, v124
	v_exp_f32_e32 v129, v33
	v_sub_f32_e32 v33, v55, v124
	v_exp_f32_e32 v130, v33
	v_sub_f32_e32 v33, v39, v124
	v_exp_f32_e32 v52, v33
	v_sub_f32_e32 v33, v56, v124
	v_exp_f32_e32 v138, v33
	v_sub_f32_e32 v33, v40, v124
	v_exp_f32_e32 v35, v33
	v_sub_f32_e32 v33, v57, v124
	v_exp_f32_e32 v54, v33
	v_sub_f32_e32 v33, v41, v124
	v_exp_f32_e32 v36, v33
	v_sub_f32_e32 v33, v58, v124
	v_exp_f32_e32 v139, v33
	v_sub_f32_e32 v33, v42, v124
	v_exp_f32_e32 v128, v33
	v_sub_f32_e32 v33, v59, v124
	v_exp_f32_e32 v56, v33
	v_sub_f32_e32 v33, v43, v124
	v_exp_f32_e32 v38, v33
	v_sub_f32_e32 v33, v60, v124
	v_exp_f32_e32 v140, v33
	v_sub_f32_e32 v33, v44, v124
	v_exp_f32_e32 v60, v33
	v_sub_f32_e32 v33, v61, v124
	v_exp_f32_e32 v58, v33
	v_sub_f32_e32 v33, v45, v124
	v_exp_f32_e32 v40, v33
	v_sub_f32_e32 v33, v62, v124
	v_exp_f32_e32 v32, v32
	v_exp_f32_e32 v61, v33
	v_sub_f32_e32 v33, v46, v124
	v_exp_f32_e32 v46, v33
	v_sub_f32_e32 v33, v63, v124
	v_exp_f32_e32 v44, v33
	v_sub_f32_e32 v33, v47, v124
	v_add_f32_e32 v109, v133, v125
	v_exp_f32_e32 v42, v33
	v_mov_b32_e32 v33, v225
	v_pk_add_f32 v[62:63], v[108:109], v[32:33]
	v_add_f32_e32 v111, v134, v126
	v_pk_add_f32 v[62:63], v[62:63], v[62:63] op_sel_hi:[0,1]
	v_mov_b32_e32 v49, v63
	v_pk_add_f32 v[62:63], v[110:111], v[48:49]
	v_add_f32_e32 v113, v135, v127
	v_pk_add_f32 v[62:63], v[62:63], v[62:63] op_sel_hi:[0,1]
	v_mov_b32_e32 v51, v63
	v_pk_add_f32 v[62:63], v[112:113], v[50:51]
	v_add_f32_e32 v131, v136, v129
	v_pk_add_f32 v[62:63], v[62:63], v[62:63] op_sel_hi:[0,1]
	v_mov_b32_e32 v53, v63
	v_add3_u32 v47, s8, v116, v117
	v_exp_f32_e32 v34, v132
	v_pk_add_f32 v[62:63], v[130:131], v[52:53]
	v_cvt_pk_bf16_f32 v108, v133, v108
	v_cvt_pk_bf16_f32 v109, v134, v110
	v_cvt_pk_bf16_f32 v110, v135, v112
	v_cvt_pk_bf16_f32 v111, v136, v130
	ds_read_b64_tr_b16 v[130:131], v47 offset:13312
	ds_read_b64_tr_b16 v[132:133], v47 offset:14464
	ds_read_b64_tr_b16 v[134:135], v47 offset:13376
	ds_read_b64_tr_b16 v[136:137], v47 offset:14528
	v_pk_mul_f32 v[14:15], v[14:15], v[34:35] op_sel_hi:[1,0]
	v_pk_mul_f32 v[12:13], v[12:13], v[34:35] op_sel_hi:[1,0]
	v_pk_mul_f32 v[10:11], v[10:11], v[34:35] op_sel_hi:[1,0]
	v_pk_mul_f32 v[8:9], v[8:9], v[34:35] op_sel_hi:[1,0]
	v_pk_mul_f32 v[6:7], v[6:7], v[34:35] op_sel_hi:[1,0]
	v_pk_mul_f32 v[4:5], v[4:5], v[34:35] op_sel_hi:[1,0]
	v_pk_mul_f32 v[2:3], v[2:3], v[34:35] op_sel_hi:[1,0]
	v_pk_mul_f32 v[0:1], v[0:1], v[34:35] op_sel_hi:[1,0]
	v_pk_mul_f32 v[30:31], v[30:31], v[34:35] op_sel_hi:[1,0]
	v_pk_mul_f32 v[28:29], v[28:29], v[34:35] op_sel_hi:[1,0]
	v_pk_mul_f32 v[26:27], v[26:27], v[34:35] op_sel_hi:[1,0]
	v_pk_mul_f32 v[24:25], v[24:25], v[34:35] op_sel_hi:[1,0]
	v_pk_mul_f32 v[22:23], v[22:23], v[34:35] op_sel_hi:[1,0]
	v_pk_mul_f32 v[20:21], v[20:21], v[34:35] op_sel_hi:[1,0]
	v_pk_mul_f32 v[18:19], v[18:19], v[34:35] op_sel_hi:[1,0]
	v_pk_mul_f32 v[16:17], v[16:17], v[34:35] op_sel_hi:[1,0]
	s_waitcnt lgkmcnt(2)
	v_mfma_f32_32x32x16_bf16 v[0:15], v[130:133], v[108:111], v[0:15]
	v_pk_add_f32 v[62:63], v[62:63], v[62:63] op_sel_hi:[0,1]
	v_add_f32_e32 v55, v138, v35
	v_mov_b32_e32 v37, v63
	v_pk_add_f32 v[62:63], v[54:55], v[36:37]
	v_add_f32_e32 v57, v139, v128
	v_pk_add_f32 v[62:63], v[62:63], v[62:63] op_sel_hi:[0,1]
	v_mov_b32_e32 v39, v63
	s_waitcnt lgkmcnt(0)
	v_mfma_f32_32x32x16_bf16 v[16:31], v[134:137], v[108:111], v[16:31]
	ds_read_b64_tr_b16 v[108:109], v47 offset:15616
	ds_read_b64_tr_b16 v[110:111], v47 offset:16768
	ds_read_b64_tr_b16 v[130:131], v47 offset:15680
	ds_read_b64_tr_b16 v[132:133], v47 offset:16832
	v_add_f32_e64 v62, v56, v38
	v_add_f32_e64 v63, v57, v39
	v_cvt_pk_bf16_f32 v54, v138, v54
	v_cvt_pk_bf16_f32 v55, v139, v56
	v_cvt_pk_bf16_f32 v56, v140, v58
	v_cvt_pk_bf16_f32 v57, v61, v44
	v_pk_add_f32 v[62:63], v[62:63], v[62:63] op_sel_hi:[0,1]
	v_add_f32_e32 v59, v140, v60
	s_waitcnt lgkmcnt(2)
	v_mfma_f32_32x32x16_bf16 v[0:15], v[108:111], v[54:57], v[0:15]
	v_mov_b32_e32 v41, v63
	v_add_f32_e64 v62, v58, v40
	v_add_f32_e64 v63, v59, v41
	v_add_f32_e32 v45, v61, v46
	v_pk_add_f32 v[62:63], v[62:63], v[62:63] op_sel_hi:[0,1]
	v_mov_b32_e32 v43, v63
	v_pk_add_f32 v[62:63], v[44:45], v[42:43]
	v_cvt_pk_bf16_f32 v37, v128, v38
	s_waitcnt lgkmcnt(0)
	v_mfma_f32_32x32x16_bf16 v[16:31], v[130:133], v[54:57], v[16:31]
	v_cvt_pk_bf16_f32 v55, v126, v48
	v_cvt_pk_bf16_f32 v56, v127, v50
	ds_read_b64_tr_b16 v[48:49], v47 offset:17920
	ds_read_b64_tr_b16 v[50:51], v47 offset:19072
	ds_read_b64_tr_b16 v[108:109], v47 offset:17984
	ds_read_b64_tr_b16 v[110:111], v47 offset:19136
	v_cvt_pk_bf16_f32 v54, v125, v32
	v_cvt_pk_bf16_f32 v57, v129, v52
	v_cvt_pk_bf16_f32 v38, v60, v40
	v_cvt_pk_bf16_f32 v39, v46, v42
	s_waitcnt lgkmcnt(2)
	v_mfma_f32_32x32x16_bf16 v[0:15], v[48:51], v[54:57], v[0:15]
	ds_read_b64_tr_b16 v[40:41], v47 offset:20224
	ds_read_b64_tr_b16 v[42:43], v47 offset:21376
	ds_read_b64_tr_b16 v[44:45], v47 offset:20288
	ds_read_b64_tr_b16 v[46:47], v47 offset:21440
	v_cvt_pk_bf16_f32 v36, v35, v36
	v_add_f32_e32 v33, v62, v63
	v_fmac_f32_e32 v33, v115, v34
	v_mov_b32_e32 v115, v33
	s_waitcnt lgkmcnt(4)
	v_mfma_f32_32x32x16_bf16 v[16:31], v[108:111], v[54:57], v[16:31]
	v_mov_b32_e32 v108, v124
	s_waitcnt lgkmcnt(2)
	v_mfma_f32_32x32x16_bf16 v[0:15], v[40:43], v[36:39], v[0:15]
	s_waitcnt lgkmcnt(0)
	v_mfma_f32_32x32x16_bf16 v[16:31], v[44:47], v[36:39], v[16:31]
